# expand_job (both copies): second batch of 4 Ktau loads issued with the first (counted waits)
# baseline (speedup 1.0000x reference)
.LBB0_1018:
	s_ashr_i32 s1, s0, 5
	s_and_b32 s4, s0, 31
	v_mov_b32_e32 v2, v208
	s_lshl_b32 s2, s1, 9
	s_lshl_b32 s3, s4, 4
	s_or_b32 s2, s2, s3
	v_ashrrev_i32_e32 v0, 4, v2
	v_add_u32_e32 v4, s2, v0
	v_readlane_b32 s2, v253, 18
	v_readlane_b32 s3, v253, 19
	s_mul_i32 s1, s1, 63
	v_and_b32_e32 v3, 15, v2
	v_mov_b64_e32 v[0:1], s[2:3]
	s_add_i32 s1, s4, s1
	v_mad_i64_i32 v[0:1], s[2:3], v4, s68, v[0:1]
	v_lshlrev_b32_e32 v192, 6, v3
	s_add_i32 s1, s1, 31
	v_lshlrev_b32_e32 v22, 1, v3
	v_lshl_add_u64 v[8:9], v[0:1], 0, v[192:193]
	v_and_b32_e32 v0, -16, v2
	v_sub_u32_e32 v2, s1, v22
	v_ashrrev_i32_e32 v3, 31, v2
	v_readlane_b32 s2, v253, 20
	v_ashrrev_i32_e32 v1, 31, v0
	v_lshlrev_b64 v[2:3], 10, v[2:3]
	v_readlane_b32 s3, v253, 21
	v_lshlrev_b64 v[0:1], 2, v[0:1]
	s_add_i32 s0, s0, s93
	v_lshl_add_u64 v[2:3], s[2:3], 0, v[2:3]
	v_lshl_add_u64 v[6:7], v[2:3], 0, v[0:1]
	global_load_dwordx4 v[2:5], v[6:7], off offset:48
	global_load_dwordx4 v[10:13], v[6:7], off offset:32
	global_load_dwordx4 v[14:17], v[6:7], off offset:16
	global_load_dwordx4 v[18:21], v[6:7], off
	v_xad_u32 v23, v22, -1, s1
	v_ashrrev_i32_e32 v24, 31, v23
	v_mov_b32_e32 v26, v23
	v_mov_b32_e32 v27, v24
	v_lshlrev_b64 v[28:29], 10, v[26:27]
	v_lshl_add_u64 v[24:25], s[2:3], 0, v[28:29]
	v_lshl_add_u64 v[26:27], v[24:25], 0, v[0:1]
	global_load_dwordx4 v[28:31], v[26:27], off offset:48
	global_load_dwordx4 v[32:35], v[26:27], off offset:32
	global_load_dwordx4 v[36:39], v[26:27], off offset:16
	global_load_dwordx4 v[40:43], v[26:27], off
	s_cmpk_gt_i32 s0, 0x2ff
	s_waitcnt vmcnt(4)
	v_and_b32_sdwa v6, v20, v218 dst_sel:DWORD dst_unused:UNUSED_PAD src0_sel:WORD_1 src1_sel:DWORD
	v_and_b32_sdwa v7, v18, v218 dst_sel:DWORD dst_unused:UNUSED_PAD src0_sel:WORD_1 src1_sel:DWORD
	v_add3_u32 v7, v18, v7, s80
	v_add3_u32 v6, v20, v6, s80
	v_and_b32_sdwa v18, v21, v218 dst_sel:DWORD dst_unused:UNUSED_PAD src0_sel:WORD_1 src1_sel:DWORD
	v_and_b32_sdwa v20, v19, v218 dst_sel:DWORD dst_unused:UNUSED_PAD src0_sel:WORD_1 src1_sel:DWORD
	v_add3_u32 v18, v21, v18, s80
	v_add3_u32 v19, v19, v20, s80
	v_and_b32_e32 v18, 0xffff0000, v18
	v_and_b32_e32 v20, 0xffff0000, v19
	v_or_b32_sdwa v19, v18, v6 dst_sel:DWORD dst_unused:UNUSED_PAD src0_sel:DWORD src1_sel:WORD_1
	v_or_b32_sdwa v18, v20, v7 dst_sel:DWORD dst_unused:UNUSED_PAD src0_sel:DWORD src1_sel:WORD_1
	v_cvt_pk_bf16_f32 v20, v14, v15
	v_cvt_pk_bf16_f32 v21, v16, v17
	v_and_b32_sdwa v6, v12, v218 dst_sel:DWORD dst_unused:UNUSED_PAD src0_sel:WORD_1 src1_sel:DWORD
	v_and_b32_sdwa v7, v10, v218 dst_sel:DWORD dst_unused:UNUSED_PAD src0_sel:WORD_1 src1_sel:DWORD
	v_add3_u32 v7, v10, v7, s80
	v_add3_u32 v6, v12, v6, s80
	v_and_b32_sdwa v10, v13, v218 dst_sel:DWORD dst_unused:UNUSED_PAD src0_sel:WORD_1 src1_sel:DWORD
	v_and_b32_sdwa v12, v11, v218 dst_sel:DWORD dst_unused:UNUSED_PAD src0_sel:WORD_1 src1_sel:DWORD
	v_add3_u32 v10, v13, v10, s80
	v_add3_u32 v11, v11, v12, s80
	v_and_b32_e32 v10, 0xffff0000, v10
	v_and_b32_e32 v12, 0xffff0000, v11
	v_or_b32_sdwa v11, v10, v6 dst_sel:DWORD dst_unused:UNUSED_PAD src0_sel:DWORD src1_sel:WORD_1
	v_or_b32_sdwa v10, v12, v7 dst_sel:DWORD dst_unused:UNUSED_PAD src0_sel:DWORD src1_sel:WORD_1
	v_cvt_pk_bf16_f32 v12, v2, v3
	v_cvt_pk_bf16_f32 v13, v4, v5
	v_xad_u32 v2, v22, -1, s1
	v_ashrrev_i32_e32 v3, 31, v2
	v_lshlrev_b64 v[2:3], 10, v[2:3]
	v_lshl_add_u64 v[2:3], s[2:3], 0, v[2:3]
	global_store_dwordx4 v[8:9], v[18:21], off
	global_store_dwordx4 v[8:9], v[10:13], off offset:16
	v_lshl_add_u64 v[14:15], v[2:3], 0, v[0:1]
	s_nop 0
	s_waitcnt vmcnt(2)
	v_mov_b32_e32 v0, v28
	v_mov_b32_e32 v1, v29
	v_mov_b32_e32 v2, v30
	v_mov_b32_e32 v3, v31
	v_mov_b32_e32 v4, v32
	v_mov_b32_e32 v5, v33
	v_mov_b32_e32 v6, v34
	v_mov_b32_e32 v7, v35
	v_mov_b32_e32 v10, v36
	v_mov_b32_e32 v11, v37
	v_mov_b32_e32 v12, v38
	v_mov_b32_e32 v13, v39
	v_mov_b32_e32 v14, v40
	v_mov_b32_e32 v15, v41
	v_mov_b32_e32 v16, v42
	v_mov_b32_e32 v17, v43
	v_and_b32_sdwa v18, v16, v218 dst_sel:DWORD dst_unused:UNUSED_PAD src0_sel:WORD_1 src1_sel:DWORD
	v_cvt_pk_bf16_f32 v14, v14, v15
	v_add3_u32 v16, v16, v18, s80
	v_and_b32_sdwa v18, v17, v218 dst_sel:DWORD dst_unused:UNUSED_PAD src0_sel:WORD_1 src1_sel:DWORD
	v_add3_u32 v17, v17, v18, s80
	v_and_b32_e32 v17, 0xffff0000, v17
	v_or_b32_sdwa v15, v17, v16 dst_sel:DWORD dst_unused:UNUSED_PAD src0_sel:DWORD src1_sel:WORD_1
	v_and_b32_sdwa v17, v10, v218 dst_sel:DWORD dst_unused:UNUSED_PAD src0_sel:WORD_1 src1_sel:DWORD
	v_add3_u32 v10, v10, v17, s80
	v_and_b32_sdwa v17, v11, v218 dst_sel:DWORD dst_unused:UNUSED_PAD src0_sel:WORD_1 src1_sel:DWORD
	v_and_b32_sdwa v16, v12, v218 dst_sel:DWORD dst_unused:UNUSED_PAD src0_sel:WORD_1 src1_sel:DWORD
	v_add3_u32 v11, v11, v17, s80
	v_add3_u32 v12, v12, v16, s80
	v_and_b32_sdwa v16, v13, v218 dst_sel:DWORD dst_unused:UNUSED_PAD src0_sel:WORD_1 src1_sel:DWORD
	v_and_b32_e32 v11, 0xffff0000, v11
	v_add3_u32 v13, v13, v16, s80
	v_or_b32_sdwa v16, v11, v10 dst_sel:DWORD dst_unused:UNUSED_PAD src0_sel:DWORD src1_sel:WORD_1
	v_and_b32_sdwa v10, v6, v218 dst_sel:DWORD dst_unused:UNUSED_PAD src0_sel:WORD_1 src1_sel:DWORD
	v_cvt_pk_bf16_f32 v4, v4, v5
	v_add3_u32 v6, v6, v10, s80
	v_and_b32_sdwa v10, v7, v218 dst_sel:DWORD dst_unused:UNUSED_PAD src0_sel:WORD_1 src1_sel:DWORD
	v_add3_u32 v7, v7, v10, s80
	v_and_b32_e32 v7, 0xffff0000, v7
	v_or_b32_sdwa v5, v7, v6 dst_sel:DWORD dst_unused:UNUSED_PAD src0_sel:DWORD src1_sel:WORD_1
	v_and_b32_sdwa v6, v2, v218 dst_sel:DWORD dst_unused:UNUSED_PAD src0_sel:WORD_1 src1_sel:DWORD
	v_and_b32_sdwa v7, v0, v218 dst_sel:DWORD dst_unused:UNUSED_PAD src0_sel:WORD_1 src1_sel:DWORD
	v_add3_u32 v0, v0, v7, s80
	v_add3_u32 v2, v2, v6, s80
	v_and_b32_sdwa v6, v3, v218 dst_sel:DWORD dst_unused:UNUSED_PAD src0_sel:WORD_1 src1_sel:DWORD
	v_and_b32_sdwa v7, v1, v218 dst_sel:DWORD dst_unused:UNUSED_PAD src0_sel:WORD_1 src1_sel:DWORD
	v_and_b32_e32 v13, 0xffff0000, v13
	v_add3_u32 v3, v3, v6, s80
	v_add3_u32 v1, v1, v7, s80
	v_or_b32_sdwa v17, v13, v12 dst_sel:DWORD dst_unused:UNUSED_PAD src0_sel:DWORD src1_sel:WORD_1
	v_and_b32_e32 v3, 0xffff0000, v3
	v_and_b32_e32 v1, 0xffff0000, v1
	v_or_b32_sdwa v7, v3, v2 dst_sel:DWORD dst_unused:UNUSED_PAD src0_sel:DWORD src1_sel:WORD_1
	v_or_b32_sdwa v6, v1, v0 dst_sel:DWORD dst_unused:UNUSED_PAD src0_sel:DWORD src1_sel:WORD_1
	global_store_dwordx4 v[8:9], v[14:17], off offset:32
	global_store_dwordx4 v[8:9], v[4:7], off offset:48
	s_cbranch_scc0 .LBB0_1018

.LBB0_1036:
	s_ashr_i32 s1, s0, 5
	v_mov_b32_e32 v2, v208
	s_and_b32 s2, s0, 31
	s_lshl_b32 s3, s1, 9
	s_mul_i32 s1, s1, 63
	s_lshl_b32 s4, s2, 4
	v_and_b32_e32 v4, 15, v2
	s_add_i32 s1, s2, s1
	v_ashrrev_i32_e32 v3, 4, v2
	s_or_b32 s3, s3, s4
	s_add_i32 s1, s1, 31
	v_lshlrev_b32_e32 v6, 1, v4
	v_mov_b64_e32 v[0:1], s[6:7]
	v_add_u32_e32 v5, s3, v3
	v_lshlrev_b32_e32 v192, 6, v4
	v_sub_u32_e32 v4, s1, v6
	v_and_b32_e32 v2, -16, v2
	v_mad_i64_i32 v[0:1], s[2:3], v5, s68, v[0:1]
	v_xad_u32 v6, v6, -1, s1
	v_ashrrev_i32_e32 v5, 31, v4
	v_ashrrev_i32_e32 v3, 31, v2
	v_lshl_add_u64 v[16:17], v[0:1], 0, v[192:193]
	v_ashrrev_i32_e32 v7, 31, v6
	v_lshlrev_b64 v[0:1], 10, v[4:5]
	v_lshlrev_b64 v[2:3], 2, v[2:3]
	v_lshlrev_b64 v[4:5], 10, v[6:7]
	v_lshl_add_u64 v[0:1], s[8:9], 0, v[0:1]
	v_lshl_add_u64 v[4:5], s[8:9], 0, v[4:5]
	v_lshl_add_u64 v[12:13], v[0:1], 0, v[2:3]
	v_lshl_add_u64 v[18:19], v[4:5], 0, v[2:3]
	global_load_dwordx4 v[0:3], v[12:13], off
	global_load_dwordx4 v[4:7], v[12:13], off offset:16
	global_load_dwordx4 v[8:11], v[12:13], off offset:32
	s_nop 0
	global_load_dwordx4 v[12:15], v[12:13], off offset:48
	global_load_dwordx4 v[36:39], v[18:19], off
	global_load_dwordx4 v[40:43], v[18:19], off offset:16
	global_load_dwordx4 v[44:47], v[18:19], off offset:32
	global_load_dwordx4 v[48:51], v[18:19], off offset:48
	s_add_i32 s0, s0, s93
	s_cmpk_gt_i32 s0, 0x2ff
	s_waitcnt vmcnt(7)
	v_and_b32_sdwa v22, v3, v218 dst_sel:DWORD dst_unused:UNUSED_PAD src0_sel:WORD_1 src1_sel:DWORD
	s_waitcnt vmcnt(6)
	v_and_b32_sdwa v26, v7, v218 dst_sel:DWORD dst_unused:UNUSED_PAD src0_sel:WORD_1 src1_sel:DWORD
	v_and_b32_sdwa v27, v5, v218 dst_sel:DWORD dst_unused:UNUSED_PAD src0_sel:WORD_1 src1_sel:DWORD
	v_and_b32_sdwa v20, v2, v218 dst_sel:DWORD dst_unused:UNUSED_PAD src0_sel:WORD_1 src1_sel:DWORD
	v_cvt_pk_bf16_f32 v0, v0, v1
	v_and_b32_sdwa v24, v6, v218 dst_sel:DWORD dst_unused:UNUSED_PAD src0_sel:WORD_1 src1_sel:DWORD
	v_and_b32_sdwa v25, v4, v218 dst_sel:DWORD dst_unused:UNUSED_PAD src0_sel:WORD_1 src1_sel:DWORD
	s_waitcnt vmcnt(5)
	v_and_b32_sdwa v30, v11, v218 dst_sel:DWORD dst_unused:UNUSED_PAD src0_sel:WORD_1 src1_sel:DWORD
	v_and_b32_sdwa v31, v9, v218 dst_sel:DWORD dst_unused:UNUSED_PAD src0_sel:WORD_1 src1_sel:DWORD
	s_waitcnt vmcnt(4)
	v_and_b32_sdwa v34, v15, v218 dst_sel:DWORD dst_unused:UNUSED_PAD src0_sel:WORD_1 src1_sel:DWORD
	v_and_b32_sdwa v35, v13, v218 dst_sel:DWORD dst_unused:UNUSED_PAD src0_sel:WORD_1 src1_sel:DWORD
	v_add3_u32 v3, v3, v22, s80
	v_add3_u32 v7, v7, v26, s80
	v_add3_u32 v5, v5, v27, s80
	v_and_b32_sdwa v28, v10, v218 dst_sel:DWORD dst_unused:UNUSED_PAD src0_sel:WORD_1 src1_sel:DWORD
	v_and_b32_sdwa v29, v8, v218 dst_sel:DWORD dst_unused:UNUSED_PAD src0_sel:WORD_1 src1_sel:DWORD
	v_and_b32_sdwa v32, v14, v218 dst_sel:DWORD dst_unused:UNUSED_PAD src0_sel:WORD_1 src1_sel:DWORD
	v_and_b32_sdwa v33, v12, v218 dst_sel:DWORD dst_unused:UNUSED_PAD src0_sel:WORD_1 src1_sel:DWORD
	v_add3_u32 v2, v2, v20, s80
	v_add3_u32 v4, v4, v25, s80
	v_add3_u32 v6, v6, v24, s80
	v_add3_u32 v11, v11, v30, s80
	v_add3_u32 v9, v9, v31, s80
	v_add3_u32 v15, v15, v34, s80
	v_add3_u32 v13, v13, v35, s80
	v_and_b32_e32 v3, 0xffff0000, v3
	v_and_b32_e32 v7, 0xffff0000, v7
	v_and_b32_e32 v5, 0xffff0000, v5
	v_add3_u32 v8, v8, v29, s80
	v_add3_u32 v10, v10, v28, s80
	v_add3_u32 v12, v12, v33, s80
	v_add3_u32 v14, v14, v32, s80
	v_and_b32_e32 v11, 0xffff0000, v11
	v_and_b32_e32 v9, 0xffff0000, v9
	v_and_b32_e32 v15, 0xffff0000, v15
	v_and_b32_e32 v13, 0xffff0000, v13
	v_or_b32_sdwa v1, v3, v2 dst_sel:DWORD dst_unused:UNUSED_PAD src0_sel:DWORD src1_sel:WORD_1
	v_or_b32_sdwa v3, v7, v6 dst_sel:DWORD dst_unused:UNUSED_PAD src0_sel:DWORD src1_sel:WORD_1
	v_or_b32_sdwa v2, v5, v4 dst_sel:DWORD dst_unused:UNUSED_PAD src0_sel:DWORD src1_sel:WORD_1
	v_or_b32_sdwa v5, v11, v10 dst_sel:DWORD dst_unused:UNUSED_PAD src0_sel:DWORD src1_sel:WORD_1
	v_or_b32_sdwa v4, v9, v8 dst_sel:DWORD dst_unused:UNUSED_PAD src0_sel:DWORD src1_sel:WORD_1
	v_or_b32_sdwa v7, v15, v14 dst_sel:DWORD dst_unused:UNUSED_PAD src0_sel:DWORD src1_sel:WORD_1
	v_or_b32_sdwa v6, v13, v12 dst_sel:DWORD dst_unused:UNUSED_PAD src0_sel:DWORD src1_sel:WORD_1
	global_store_dwordx4 v[16:17], v[0:3], off
	global_store_dwordx4 v[16:17], v[4:7], off offset:16
	s_nop 0
	s_waitcnt vmcnt(5)
	v_mov_b32_e32 v0, v36
	v_mov_b32_e32 v1, v37
	v_mov_b32_e32 v2, v38
	v_mov_b32_e32 v3, v39
	v_and_b32_sdwa v20, v3, v218 dst_sel:DWORD dst_unused:UNUSED_PAD src0_sel:WORD_1 src1_sel:DWORD
	s_waitcnt vmcnt(4)
	v_mov_b32_e32 v4, v40
	v_mov_b32_e32 v5, v41
	v_mov_b32_e32 v6, v42
	v_mov_b32_e32 v7, v43
	v_and_b32_sdwa v24, v7, v218 dst_sel:DWORD dst_unused:UNUSED_PAD src0_sel:WORD_1 src1_sel:DWORD
	v_and_b32_sdwa v25, v5, v218 dst_sel:DWORD dst_unused:UNUSED_PAD src0_sel:WORD_1 src1_sel:DWORD
	v_and_b32_sdwa v18, v2, v218 dst_sel:DWORD dst_unused:UNUSED_PAD src0_sel:WORD_1 src1_sel:DWORD
	v_cvt_pk_bf16_f32 v0, v0, v1
	v_and_b32_sdwa v22, v6, v218 dst_sel:DWORD dst_unused:UNUSED_PAD src0_sel:WORD_1 src1_sel:DWORD
	v_and_b32_sdwa v23, v4, v218 dst_sel:DWORD dst_unused:UNUSED_PAD src0_sel:WORD_1 src1_sel:DWORD
	s_waitcnt vmcnt(3)
	v_mov_b32_e32 v8, v44
	v_mov_b32_e32 v9, v45
	v_mov_b32_e32 v10, v46
	v_mov_b32_e32 v11, v47
	v_and_b32_sdwa v28, v11, v218 dst_sel:DWORD dst_unused:UNUSED_PAD src0_sel:WORD_1 src1_sel:DWORD
	v_and_b32_sdwa v29, v9, v218 dst_sel:DWORD dst_unused:UNUSED_PAD src0_sel:WORD_1 src1_sel:DWORD
	s_waitcnt vmcnt(2)
	v_mov_b32_e32 v12, v48
	v_mov_b32_e32 v13, v49
	v_mov_b32_e32 v14, v50
	v_mov_b32_e32 v15, v51
	v_and_b32_sdwa v32, v15, v218 dst_sel:DWORD dst_unused:UNUSED_PAD src0_sel:WORD_1 src1_sel:DWORD
	v_and_b32_sdwa v33, v13, v218 dst_sel:DWORD dst_unused:UNUSED_PAD src0_sel:WORD_1 src1_sel:DWORD
	v_add3_u32 v3, v3, v20, s80
	v_add3_u32 v7, v7, v24, s80
	v_add3_u32 v5, v5, v25, s80
	v_and_b32_sdwa v26, v10, v218 dst_sel:DWORD dst_unused:UNUSED_PAD src0_sel:WORD_1 src1_sel:DWORD
	v_and_b32_sdwa v27, v8, v218 dst_sel:DWORD dst_unused:UNUSED_PAD src0_sel:WORD_1 src1_sel:DWORD
	v_and_b32_sdwa v30, v14, v218 dst_sel:DWORD dst_unused:UNUSED_PAD src0_sel:WORD_1 src1_sel:DWORD
	v_and_b32_sdwa v31, v12, v218 dst_sel:DWORD dst_unused:UNUSED_PAD src0_sel:WORD_1 src1_sel:DWORD
	v_add3_u32 v2, v2, v18, s80
	v_add3_u32 v4, v4, v23, s80
	v_add3_u32 v6, v6, v22, s80
	v_add3_u32 v11, v11, v28, s80
	v_add3_u32 v9, v9, v29, s80
	v_add3_u32 v15, v15, v32, s80
	v_add3_u32 v13, v13, v33, s80
	v_and_b32_e32 v3, 0xffff0000, v3
	v_and_b32_e32 v7, 0xffff0000, v7
	v_and_b32_e32 v5, 0xffff0000, v5
	v_add3_u32 v8, v8, v27, s80
	v_add3_u32 v10, v10, v26, s80
	v_add3_u32 v12, v12, v31, s80
	v_add3_u32 v14, v14, v30, s80
	v_and_b32_e32 v11, 0xffff0000, v11
	v_and_b32_e32 v9, 0xffff0000, v9
	v_and_b32_e32 v15, 0xffff0000, v15
	v_and_b32_e32 v13, 0xffff0000, v13
	v_or_b32_sdwa v1, v3, v2 dst_sel:DWORD dst_unused:UNUSED_PAD src0_sel:DWORD src1_sel:WORD_1
	v_or_b32_sdwa v3, v7, v6 dst_sel:DWORD dst_unused:UNUSED_PAD src0_sel:DWORD src1_sel:WORD_1
	v_or_b32_sdwa v2, v5, v4 dst_sel:DWORD dst_unused:UNUSED_PAD src0_sel:DWORD src1_sel:WORD_1
	v_or_b32_sdwa v5, v11, v10 dst_sel:DWORD dst_unused:UNUSED_PAD src0_sel:DWORD src1_sel:WORD_1
	v_or_b32_sdwa v4, v9, v8 dst_sel:DWORD dst_unused:UNUSED_PAD src0_sel:DWORD src1_sel:WORD_1
	v_or_b32_sdwa v7, v15, v14 dst_sel:DWORD dst_unused:UNUSED_PAD src0_sel:DWORD src1_sel:WORD_1
	v_or_b32_sdwa v6, v13, v12 dst_sel:DWORD dst_unused:UNUSED_PAD src0_sel:DWORD src1_sel:WORD_1
	global_store_dwordx4 v[16:17], v[0:3], off offset:32
	global_store_dwordx4 v[16:17], v[4:7], off offset:48
	s_cbranch_scc0 .LBB0_1036
